# grid-barrier poll loops (local waiters and leaders, both barriers): back-off s_sleep 1 removed
# speedup vs baseline: 1.0022x; 1.0022x over previous
; __device__ __forceinline__ unsigned xb_ld(unsigned* p)              { return __hip_atomic_load(p, __ATOMIC_RELAXED, __HIP_MEMORY_SCOPE_AGENT); }
; __device__ __forceinline__ unsigned xb_add(unsigned* p, unsigned v) { return __hip_atomic_fetch_add(p, v, __ATOMIC_RELAXED, __HIP_MEMORY_SCOPE_AGENT); }
; #define XB_SPIN(cond, bar) do { unsigned _sp = 0; while (cond) { __builtin_amdgcn_s_sleep(1); \
;     if ((++_sp & 255u) == 0u) { if (xb_ld(&(bar)[XB_TMO])) break; if (_sp > XB_SPIN_CAP) { atomicAdd(&(bar)[XB_TMO], 1u); break; } } } } while (0)
; __device__ __forceinline__ void xcd_barrier(const XcdBarrier& b) {
;     ...
;             else XB_SPIN(xb_ld(&bar[XB_TOPGEN]) == tg, bar);
;             __builtin_amdgcn_fence(__ATOMIC_ACQUIRE, "agent");
;             xb_add(&bar[XB_XGEN(b.x)], 1u);
;             asm volatile("s_waitcnt vmcnt(0)" ::: "memory");
;         } else {
;             XB_SPIN(xb_ld(&bar[XB_XGEN(b.x)]) == gen, bar);
.LBB0_92:
	s_and_b32 s20, s24, 0xff
	s_mov_b64 s[18:19], -1
	s_cmp_lg_u32 s20, 0
	s_mov_b64 s[22:23], -1
	s_nop 0
	s_cbranch_scc1 .LBB0_95
	global_load_dword v2, v0, s[10:11] sc1
	s_waitcnt vmcnt(0)
	v_cmp_eq_u32_e32 vcc, 0, v2
	s_cbranch_vccnz .LBB0_97
	s_mov_b64 s[22:23], 0
	s_mov_b64 s[20:21], -1

; __device__ __forceinline__ unsigned xb_ld(unsigned* p)              { return __hip_atomic_load(p, __ATOMIC_RELAXED, __HIP_MEMORY_SCOPE_AGENT); }
; __device__ __forceinline__ unsigned xb_add(unsigned* p, unsigned v) { return __hip_atomic_fetch_add(p, v, __ATOMIC_RELAXED, __HIP_MEMORY_SCOPE_AGENT); }
; #define XB_SPIN(cond, bar) do { unsigned _sp = 0; while (cond) { __builtin_amdgcn_s_sleep(1); \
;     if ((++_sp & 255u) == 0u) { if (xb_ld(&(bar)[XB_TMO])) break; if (_sp > XB_SPIN_CAP) { atomicAdd(&(bar)[XB_TMO], 1u); break; } } } } while (0)
; __device__ __forceinline__ void xcd_barrier(const XcdBarrier& b) {
;     ...
;             else XB_SPIN(xb_ld(&bar[XB_TOPGEN]) == tg, bar);
;             __builtin_amdgcn_fence(__ATOMIC_ACQUIRE, "agent");
;             xb_add(&bar[XB_XGEN(b.x)], 1u);
;             asm volatile("s_waitcnt vmcnt(0)" ::: "memory");
;         } else {
;             XB_SPIN(xb_ld(&bar[XB_XGEN(b.x)]) == gen, bar);
.LBB0_109:
	s_and_b32 s18, s24, 0xff
	s_cmp_lg_u32 s18, 0
	s_mov_b64 s[20:21], -1
	s_nop 0
	s_cbranch_scc1 .LBB0_112
	global_load_dword v1, v0, s[10:11] sc1
	s_waitcnt vmcnt(0)
	v_cmp_eq_u32_e32 vcc, 0, v1
	s_cbranch_vccnz .LBB0_114
	s_mov_b64 s[20:21], 0
	s_mov_b64 s[18:19], -1

; __device__ __forceinline__ unsigned xb_ld(unsigned* p)              { return __hip_atomic_load(p, __ATOMIC_RELAXED, __HIP_MEMORY_SCOPE_AGENT); }
; __device__ __forceinline__ unsigned xb_add(unsigned* p, unsigned v) { return __hip_atomic_fetch_add(p, v, __ATOMIC_RELAXED, __HIP_MEMORY_SCOPE_AGENT); }
; #define XB_SPIN(cond, bar) do { unsigned _sp = 0; while (cond) { __builtin_amdgcn_s_sleep(1); \
;     if ((++_sp & 255u) == 0u) { if (xb_ld(&(bar)[XB_TMO])) break; if (_sp > XB_SPIN_CAP) { atomicAdd(&(bar)[XB_TMO], 1u); break; } } } } while (0)
; __device__ __forceinline__ void xcd_barrier(const XcdBarrier& b) {
;     ...
;             else XB_SPIN(xb_ld(&bar[XB_TOPGEN]) == tg, bar);
;             __builtin_amdgcn_fence(__ATOMIC_ACQUIRE, "agent");
;             xb_add(&bar[XB_XGEN(b.x)], 1u);
;             asm volatile("s_waitcnt vmcnt(0)" ::: "memory");
;         } else {
;             XB_SPIN(xb_ld(&bar[XB_XGEN(b.x)]) == gen, bar);
.LBB0_361:
	s_and_b32 s18, s22, 0xff
	s_mov_b64 s[16:17], -1
	s_cmp_lg_u32 s18, 0
	s_mov_b64 s[20:21], -1
	s_nop 0
	s_cbranch_scc1 .LBB0_364
	global_load_dword v2, v0, s[8:9] sc1
	s_waitcnt vmcnt(0)
	v_cmp_eq_u32_e32 vcc, 0, v2
	s_cbranch_vccnz .LBB0_366
	s_mov_b64 s[20:21], 0
	s_mov_b64 s[18:19], -1

; __device__ __forceinline__ unsigned xb_ld(unsigned* p)              { return __hip_atomic_load(p, __ATOMIC_RELAXED, __HIP_MEMORY_SCOPE_AGENT); }
; __device__ __forceinline__ unsigned xb_add(unsigned* p, unsigned v) { return __hip_atomic_fetch_add(p, v, __ATOMIC_RELAXED, __HIP_MEMORY_SCOPE_AGENT); }
; #define XB_SPIN(cond, bar) do { unsigned _sp = 0; while (cond) { __builtin_amdgcn_s_sleep(1); \
;     if ((++_sp & 255u) == 0u) { if (xb_ld(&(bar)[XB_TMO])) break; if (_sp > XB_SPIN_CAP) { atomicAdd(&(bar)[XB_TMO], 1u); break; } } } } while (0)
; __device__ __forceinline__ void xcd_barrier(const XcdBarrier& b) {
;     ...
;             else XB_SPIN(xb_ld(&bar[XB_TOPGEN]) == tg, bar);
;             __builtin_amdgcn_fence(__ATOMIC_ACQUIRE, "agent");
;             xb_add(&bar[XB_XGEN(b.x)], 1u);
;             asm volatile("s_waitcnt vmcnt(0)" ::: "memory");
;         } else {
;             XB_SPIN(xb_ld(&bar[XB_XGEN(b.x)]) == gen, bar);
.LBB0_378:
	s_and_b32 s16, s22, 0xff
	s_cmp_lg_u32 s16, 0
	s_mov_b64 s[18:19], -1
	s_nop 0
	s_cbranch_scc1 .LBB0_381
	global_load_dword v1, v0, s[8:9] sc1
	s_waitcnt vmcnt(0)
	v_cmp_eq_u32_e32 vcc, 0, v1
	s_cbranch_vccnz .LBB0_383
	s_mov_b64 s[18:19], 0
	s_mov_b64 s[16:17], -1
